# FFN-up epilogue slab-end row writes: LDS-vs-ZS decision taken once per row half instead of per 16-byte store (far fewer scalar/branch instructions)
# speedup vs baseline: 1.0096x; 1.0096x over previous
; #define LAS __attribute__((address_space(3)))
;     __device__ __forceinline__ void operator()(f32x4 (&acc)[2][2][4][2], const Unit& u, int wr, int wc, int fr, int fq, int next_pn) const {
;     ...
;         for (int ai = 0; ai < 2; ++ai) { const f32x4 rs4 = *(const LAS f32x4*)(R + rl0 + ai * HALF);
; #pragma unroll
;             for (int m = 0; m < 4; ++m)
; #pragma unroll
;                 for (int bj = 0; bj < 2; ++bj) { acc[ai][bj][m][0] *= rs4[m]; acc[ai][bj][m][1] *= rs4[m]; } }
; #pragma unroll
;         for (int ai = 0; ai < 2; ++ai) { const int sl = 2 * ai + wr;
;             if (fr == 15) {
; #pragma unroll
;                 for (int k = 0; k < 2; ++k)
; #pragma unroll
;                     for (int bj = 0; bj < 2; ++bj)
; #pragma unroll
;                         for (int n = 0; n < 2; ++n) {
;                             if (sl < 3) *(LAS f32x4*)(H + (sl * 2 + k) * 256 + bj * 128 + tcol + 4 * n) = acc[ai][bj][2 + k][n];
;                             else *(f32x4*)(ZS + ((size_t)u.pm * 4 + 2 + k) * 5632 + bj * FFW + c0 + 4 * n) = acc[ai][bj][2 + k][n]; } }
.LBB0_665:
	v_lshl_or_b32 v140, v206, 2, s65
	v_lshl_add_u32 v130, v140, 2, 0
	v_add_u32_e32 v131, 0x21c00, v130
	ds_read_b128 v[134:137], v131
	v_ashrrev_i32_e32 v0, 1, v207
	v_and_b32_e32 v0, -8, v0
	v_add_u32_e32 v0, s66, v0
	v_add_u32_e32 v202, s10, v0
	s_waitcnt lgkmcnt(0)
	v_mov_b32_e32 v130, v137
	v_pk_mul_f32 v[128:129], v[128:129], v[130:131] op_sel_hi:[1,0]
	v_pk_mul_f32 v[126:127], v[126:127], v[130:131] op_sel_hi:[1,0]
	v_pk_mul_f32 v[72:73], v[72:73], v[130:131] op_sel_hi:[1,0]
	v_pk_mul_f32 v[70:71], v[70:71], v[130:131] op_sel_hi:[1,0]
	v_pk_mul_f32 v[124:125], v[124:125], v[130:131] op_sel_hi:[1,0]
	v_pk_mul_f32 v[122:123], v[122:123], v[130:131] op_sel_hi:[1,0]
	v_pk_mul_f32 v[68:69], v[68:69], v[130:131] op_sel_hi:[1,0]
	v_pk_mul_f32 v[66:67], v[66:67], v[130:131] op_sel_hi:[1,0]
	ds_read_b128 v[130:133], v131 offset:512
	v_pk_mul_f32 v[116:117], v[116:117], v[136:137] op_sel_hi:[1,0]
	v_pk_mul_f32 v[114:115], v[114:115], v[136:137] op_sel_hi:[1,0]
	v_pk_mul_f32 v[64:65], v[64:65], v[136:137] op_sel_hi:[1,0]
	v_pk_mul_f32 v[62:63], v[62:63], v[136:137] op_sel_hi:[1,0]
	v_pk_mul_f32 v[120:121], v[120:121], v[136:137] op_sel_hi:[1,0]
	v_pk_mul_f32 v[118:119], v[118:119], v[136:137] op_sel_hi:[1,0]
	v_pk_mul_f32 v[60:61], v[60:61], v[136:137] op_sel_hi:[1,0]
	v_pk_mul_f32 v[58:59], v[58:59], v[136:137] op_sel_hi:[1,0]
	v_cmp_eq_u32_e64 s[8:9], 15, v206
	v_ashrrev_i32_e32 v203, 31, v202
	s_mul_hi_i32 s21, s89, 0x16000
	s_mul_i32 s92, s89, 0x16000
	s_and_saveexec_b64 s[46:47], s[8:9]
	s_cbranch_execz .LBB0_692
	v_lshl_add_u32 v136, v0, 2, s75
	ds_write_b128 v136, v[114:117]
	ds_write_b128 v136, v[62:65] offset:16
	ds_write_b128 v136, v[118:121] offset:512
	ds_write_b128 v136, v[58:61] offset:528
	ds_write_b128 v136, v[126:129] offset:1024
	ds_write_b128 v136, v[70:73] offset:1040
	ds_write_b128 v136, v[122:125] offset:1536
	ds_write_b128 v136, v[66:69] offset:1552
	s_branch .LBB0_692
	s_mov_b64 s[10:11], -1
	s_and_b64 vcc, exec, s[30:31]
	s_cbranch_vccz .LBB0_668
	s_add_u32 s10, s60, s92
	s_addc_u32 s11, s61, s21
	v_lshl_add_u64 v[136:137], v[202:203], 2, s[10:11]
	v_add_co_u32_e32 v136, vcc, 0xb000, v136
	s_mov_b64 s[10:11], 0
	s_nop 0
	v_addc_co_u32_e32 v137, vcc, 0, v137, vcc
	global_store_dwordx4 v[136:137], v[114:117], off

; #define LAS __attribute__((address_space(3)))
;     __device__ __forceinline__ void operator()(f32x4 (&acc)[2][2][4][2], const Unit& u, int wr, int wc, int fr, int fq, int next_pn) const {
;     ...
;         for (int ai = 0; ai < 2; ++ai) { const f32x4 rs4 = *(const LAS f32x4*)(R + rl0 + ai * HALF);
; #pragma unroll
;             for (int m = 0; m < 4; ++m)
; #pragma unroll
;                 for (int bj = 0; bj < 2; ++bj) { acc[ai][bj][m][0] *= rs4[m]; acc[ai][bj][m][1] *= rs4[m]; } }
; #pragma unroll
;         for (int ai = 0; ai < 2; ++ai) { const int sl = 2 * ai + wr;
;             if (fr == 15) {
; #pragma unroll
;                 for (int k = 0; k < 2; ++k)
; #pragma unroll
;                     for (int bj = 0; bj < 2; ++bj)
; #pragma unroll
;                         for (int n = 0; n < 2; ++n) {
;                             if (sl < 3) *(LAS f32x4*)(H + (sl * 2 + k) * 256 + bj * 128 + tcol + 4 * n) = acc[ai][bj][2 + k][n];
;                             else *(f32x4*)(ZS + ((size_t)u.pm * 4 + 2 + k) * 5632 + bj * FFW + c0 + 4 * n) = acc[ai][bj][2 + k][n]; } }
.LBB0_694:
	s_or_b64 exec, exec, s[44:45]
	s_waitcnt lgkmcnt(0)
	v_pk_mul_f32 v[52:53], v[52:53], v[132:133] op_sel_hi:[1,0]
	v_pk_mul_f32 v[50:51], v[50:51], v[132:133] op_sel_hi:[1,0]
	v_pk_mul_f32 v[4:5], v[4:5], v[132:133] op_sel_hi:[1,0]
	v_pk_mul_f32 v[2:3], v[2:3], v[132:133] op_sel_hi:[1,0]
	v_pk_mul_f32 v[56:57], v[56:57], v[132:133] op_sel_hi:[1,0]
	v_pk_mul_f32 v[54:55], v[54:55], v[132:133] op_sel_hi:[1,0]
	v_pk_mul_f32 v[8:9], v[8:9], v[132:133] op_sel_hi:[1,0]
	v_pk_mul_f32 v[6:7], v[6:7], v[132:133] op_sel_hi:[1,0]
	v_mov_b32_e32 v132, v133
	v_pk_mul_f32 v[76:77], v[76:77], v[132:133] op_sel_hi:[1,0]
	v_pk_mul_f32 v[74:75], v[74:75], v[132:133] op_sel_hi:[1,0]
	v_pk_mul_f32 v[12:13], v[12:13], v[132:133] op_sel_hi:[1,0]
	v_pk_mul_f32 v[10:11], v[10:11], v[132:133] op_sel_hi:[1,0]
	v_pk_mul_f32 v[80:81], v[80:81], v[132:133] op_sel_hi:[1,0]
	v_pk_mul_f32 v[78:79], v[78:79], v[132:133] op_sel_hi:[1,0]
	v_pk_mul_f32 v[16:17], v[16:17], v[132:133] op_sel_hi:[1,0]
	v_pk_mul_f32 v[14:15], v[14:15], v[132:133] op_sel_hi:[1,0]
	v_cndmask_b32_e64 v132, 0, 1, s[34:35]
	s_and_saveexec_b64 s[44:45], s[8:9]
	s_cbranch_execz .LBB0_733
	s_and_b64 vcc, exec, s[34:35]
	s_cbranch_vccz .Lffn_hc_lds
	s_add_u32 s46, s60, s92
	s_addc_u32 s47, s61, s21
	v_lshl_add_u64 v[134:135], v[202:203], 2, s[46:47]
	v_add_co_u32_e32 v136, vcc, 0xb000, v134
	s_nop 1
	v_addc_co_u32_e32 v137, vcc, 0, v135, vcc
	v_add_co_u32_e32 v142, vcc, 0xd000, v134
	s_nop 1
	v_addc_co_u32_e32 v143, vcc, 0, v135, vcc
	global_store_dwordx4 v[136:137], v[50:53], off
	global_store_dwordx4 v[136:137], v[2:5], off offset:16
	global_store_dwordx4 v[142:143], v[54:57], off offset:3072
	global_store_dwordx4 v[142:143], v[6:9], off offset:3088
	s_mov_b64 s[46:47], 0x5800
	v_lshl_add_u64 v[136:137], v[136:137], 0, s[46:47]
	v_lshl_add_u64 v[142:143], v[142:143], 0, s[46:47]
	global_store_dwordx4 v[136:137], v[74:77], off
	global_store_dwordx4 v[136:137], v[10:13], off offset:16
	global_store_dwordx4 v[142:143], v[78:81], off offset:3072
	global_store_dwordx4 v[142:143], v[14:17], off offset:3088
	s_branch .LBB0_733
.Lffn_hc_lds:
	v_lshl_add_u32 v133, v0, 2, s78
	ds_write_b128 v133, v[50:53]
	ds_write_b128 v133, v[2:5] offset:16
	ds_write_b128 v133, v[54:57] offset:512
	ds_write_b128 v133, v[6:9] offset:528
	ds_write_b128 v133, v[74:77] offset:1024
	ds_write_b128 v133, v[10:13] offset:1040
	ds_write_b128 v133, v[78:81] offset:1536
	ds_write_b128 v133, v[14:17] offset:1552
	s_branch .LBB0_733
	v_cmp_ne_u32_e64 s[8:9], 1, v132
	s_andn2_b64 vcc, exec, s[34:35]
	s_mov_b64 s[46:47], -1
	s_cbranch_vccnz .LBB0_709
	s_add_u32 s46, s60, s92
	s_addc_u32 s47, s61, s21
	v_lshl_add_u64 v[134:135], v[202:203], 2, s[46:47]
	v_add_co_u32_e32 v134, vcc, 0xb000, v134
	s_nop 1
	v_addc_co_u32_e32 v135, vcc, 0, v135, vcc
	global_store_dwordx4 v[134:135], v[50:53], off
	s_cbranch_execz .LBB0_710
